# v23 + Fourier channel-DFT prep items on f32 matrix cores (v_mfma_f32_32x32x2_f32, f32 operands/accumulate), transposed LDS staging with all loads up front
# speedup vs baseline: 1.0165x; 1.0060x over previous
; __device__ __forceinline__ void phase_prep(const Params& P, int l, unsigned char* lds) {
;     ...
;             float* U = (float*)lds;
;             float* U2 = U + 64 * 256;
; #pragma unroll
;             for (int rep = 0; rep < 4; ++rep) {
;                 const int id = tid + 512 * rep, tok = id >> 5, ch = id & 31;
;                 const u32x4 w = *(const u32x4*)(proj + (size_t)(r0 + tok) * INW + PD_U + 8 * ch);
;                 f32x4 a0 = (f32x4){bflo(w.x), bfhi(w.x), bflo(w.y), bfhi(w.y)}, a1 = (f32x4){bflo(w.z), bfhi(w.z), bflo(w.w), bfhi(w.w)};
;                 float* d = U + tok * 256 + 8 * ch;
;                 if (!is_ctx) {
;                     const int tg = t0 - CTX + tok, mt = (tg == 0) ? SEQ / 2 : SEQ - tg;
;                     const u32x4 m = *(const u32x4*)(proj + ((size_t)b * TT + CTX + mt) * INW + PD_U + 8 * ch);
;                     const f32x4 m0 = (f32x4){bflo(m.x), bfhi(m.x), bflo(m.y), bfhi(m.y)}, m1 = (f32x4){bflo(m.z), bfhi(m.z), bflo(m.w), bfhi(m.w)};
;                     float* d2 = U2 + tok * 256 + 8 * ch;
;                     if (tg == 0) { *(f32x4*)d2 = m0; *(f32x4*)(d2 + 4) = m1; }
;                     else { *(f32x4*)d2 = a0 - m0; *(f32x4*)(d2 + 4) = a1 - m1; a0 = a0 + m0; a1 = a1 + m1; }
;                 }
;                 *(f32x4*)d = a0; *(f32x4*)(d + 4) = a1;
;             }
.LBB0_232:
	s_cmpk_gt_i32 s64, 0xff
	s_cselect_b64 s[42:43], -1, 0
	s_cmpk_lt_i32 s64, 0x100
	s_cselect_b64 s[48:49], -1, 0
	s_andn2_b64 vcc, exec, s[38:39]
	s_mov_b64 s[38:39], -1
	s_cbranch_vccnz .LBB0_277
	v_and_b32_e32 v32, 63, v44
	v_lshrrev_b32_e32 v33, 5, v32
	v_and_b32_e32 v34, 31, v32
	v_readfirstlane_b32 s12, v44
	s_nop 3
	s_lshr_b32 s12, s12, 6
	s_and_b32 s13, s12, 1
	s_lshr_b32 s15, s12, 1
	v_add_u32_e32 v41, s29, v32
	v_mov_b64_e32 v[100:101], s[10:11]
	v_mad_u64_u32 v[102:103], s[18:19], v41, s23, v[100:101]
	s_lshl_b32 s7, s12, 6
	s_add_u32 s7, s7, 0x1400
	v_add_co_u32_e32 v102, vcc, s7, v102
	s_nop 1
	v_addc_co_u32_e32 v103, vcc, 0, v103, vcc
	global_load_dwordx4 v[0:3], v[102:103], off
	global_load_dwordx4 v[4:7], v[102:103], off offset:16
	global_load_dwordx4 v[8:11], v[102:103], off offset:32
	global_load_dwordx4 v[12:15], v[102:103], off offset:48
	s_and_b64 vcc, exec, s[42:43]
	s_cbranch_vccz .Ldft_st_ctx
	v_add_u32_e32 v42, s64, v32
	v_add_u32_e32 v42, 0xffffff00, v42
	v_sub_u32_e32 v43, 0x800, v42
	v_cmp_ne_u32_e32 vcc, 0, v42
	s_nop 1
	v_cndmask_b32_e32 v43, v242, v43, vcc
	s_mul_i32 s18, s36, 0x900
	s_add_u32 s18, s18, 0x100
	v_add_u32_e32 v43, s18, v43
	v_mad_u64_u32 v[104:105], s[18:19], v43, s23, v[100:101]
	v_add_co_u32_e32 v104, vcc, s7, v104
	s_nop 1
	v_addc_co_u32_e32 v105, vcc, 0, v105, vcc
	global_load_dwordx4 v[16:19], v[104:105], off
	global_load_dwordx4 v[20:23], v[104:105], off offset:16
	global_load_dwordx4 v[24:27], v[104:105], off offset:32
	global_load_dwordx4 v[28:31], v[104:105], off offset:48
.Ldft_st_ctx:
	s_lshl_b32 s7, s12, 13
	v_lshl_add_u32 v35, v32, 2, s7
	v_add_u32_e32 v36, 0x10000, v35
	s_waitcnt vmcnt(0)
	v_lshlrev_b32_e32 v45, 16, v0
	v_and_b32_e32 v46, 0xffff0000, v0
	v_lshlrev_b32_e32 v47, 16, v1
	v_and_b32_e32 v48, 0xffff0000, v1
	v_lshlrev_b32_e32 v49, 16, v2
	v_and_b32_e32 v50, 0xffff0000, v2
	v_lshlrev_b32_e32 v51, 16, v3
	v_and_b32_e32 v52, 0xffff0000, v3
	v_lshlrev_b32_e32 v53, 16, v4
	v_and_b32_e32 v54, 0xffff0000, v4
	v_lshlrev_b32_e32 v55, 16, v5
	v_and_b32_e32 v56, 0xffff0000, v5
	v_lshlrev_b32_e32 v57, 16, v6
	v_and_b32_e32 v58, 0xffff0000, v6
	v_lshlrev_b32_e32 v59, 16, v7
	v_and_b32_e32 v60, 0xffff0000, v7
	v_lshlrev_b32_e32 v61, 16, v8
	v_and_b32_e32 v62, 0xffff0000, v8
	v_lshlrev_b32_e32 v63, 16, v9
	v_and_b32_e32 v64, 0xffff0000, v9
	v_lshlrev_b32_e32 v65, 16, v10
	v_and_b32_e32 v66, 0xffff0000, v10
	v_lshlrev_b32_e32 v67, 16, v11
	v_and_b32_e32 v68, 0xffff0000, v11
	v_lshlrev_b32_e32 v69, 16, v12
	v_and_b32_e32 v70, 0xffff0000, v12
	v_lshlrev_b32_e32 v71, 16, v13
	v_and_b32_e32 v72, 0xffff0000, v13
	v_lshlrev_b32_e32 v73, 16, v14
	v_and_b32_e32 v74, 0xffff0000, v14
	v_lshlrev_b32_e32 v75, 16, v15
	v_and_b32_e32 v76, 0xffff0000, v15
	s_and_b64 vcc, exec, s[42:43]
	s_cbranch_vccz .Ldft_wr_u
	v_lshlrev_b32_e32 v77, 16, v16
	v_and_b32_e32 v78, 0xffff0000, v16
	v_lshlrev_b32_e32 v79, 16, v17
	v_and_b32_e32 v80, 0xffff0000, v17
	v_lshlrev_b32_e32 v81, 16, v18
	v_and_b32_e32 v82, 0xffff0000, v18
	v_lshlrev_b32_e32 v83, 16, v19
	v_and_b32_e32 v84, 0xffff0000, v19
	v_lshlrev_b32_e32 v85, 16, v20
	v_and_b32_e32 v86, 0xffff0000, v20
	v_lshlrev_b32_e32 v87, 16, v21
	v_and_b32_e32 v88, 0xffff0000, v21
	v_lshlrev_b32_e32 v89, 16, v22
	v_and_b32_e32 v90, 0xffff0000, v22
	v_lshlrev_b32_e32 v91, 16, v23
	v_and_b32_e32 v92, 0xffff0000, v23
	v_lshlrev_b32_e32 v93, 16, v24
	v_and_b32_e32 v94, 0xffff0000, v24
	v_lshlrev_b32_e32 v95, 16, v25
	v_and_b32_e32 v96, 0xffff0000, v25
	v_lshlrev_b32_e32 v97, 16, v26
	v_and_b32_e32 v98, 0xffff0000, v26
	v_lshlrev_b32_e32 v99, 16, v27
	v_and_b32_e32 v100, 0xffff0000, v27
	v_lshlrev_b32_e32 v101, 16, v28
	v_and_b32_e32 v102, 0xffff0000, v28
	v_lshlrev_b32_e32 v103, 16, v29
	v_and_b32_e32 v104, 0xffff0000, v29
	v_lshlrev_b32_e32 v105, 16, v30
	v_and_b32_e32 v106, 0xffff0000, v30
	v_lshlrev_b32_e32 v107, 16, v31
	v_and_b32_e32 v108, 0xffff0000, v31
	v_add_u32_e32 v42, s64, v32
	v_mov_b32_e32 v43, 0x100
	v_cmp_ne_u32_e64 s[50:51], v43, v42
	s_nop 1
	v_sub_f32_e32 v43, v45, v77
	v_add_f32_e32 v126, v45, v77
	v_cndmask_b32_e64 v77, v77, v43, s[50:51]
	v_cndmask_b32_e64 v45, v45, v126, s[50:51]
	v_sub_f32_e32 v43, v46, v78
	v_add_f32_e32 v126, v46, v78
	v_cndmask_b32_e64 v78, v78, v43, s[50:51]
	v_cndmask_b32_e64 v46, v46, v126, s[50:51]
	v_sub_f32_e32 v43, v47, v79
	v_add_f32_e32 v126, v47, v79
	v_cndmask_b32_e64 v79, v79, v43, s[50:51]
	v_cndmask_b32_e64 v47, v47, v126, s[50:51]
	v_sub_f32_e32 v43, v48, v80
	v_add_f32_e32 v126, v48, v80
	v_cndmask_b32_e64 v80, v80, v43, s[50:51]
	v_cndmask_b32_e64 v48, v48, v126, s[50:51]
	v_sub_f32_e32 v43, v49, v81
	v_add_f32_e32 v126, v49, v81
	v_cndmask_b32_e64 v81, v81, v43, s[50:51]
	v_cndmask_b32_e64 v49, v49, v126, s[50:51]
	v_sub_f32_e32 v43, v50, v82
	v_add_f32_e32 v126, v50, v82
	v_cndmask_b32_e64 v82, v82, v43, s[50:51]
	v_cndmask_b32_e64 v50, v50, v126, s[50:51]
	v_sub_f32_e32 v43, v51, v83
	v_add_f32_e32 v126, v51, v83
	v_cndmask_b32_e64 v83, v83, v43, s[50:51]
	v_cndmask_b32_e64 v51, v51, v126, s[50:51]
	v_sub_f32_e32 v43, v52, v84
	v_add_f32_e32 v126, v52, v84
	v_cndmask_b32_e64 v84, v84, v43, s[50:51]
	v_cndmask_b32_e64 v52, v52, v126, s[50:51]
	v_sub_f32_e32 v43, v53, v85
	v_add_f32_e32 v126, v53, v85
	v_cndmask_b32_e64 v85, v85, v43, s[50:51]
	v_cndmask_b32_e64 v53, v53, v126, s[50:51]
	v_sub_f32_e32 v43, v54, v86
	v_add_f32_e32 v126, v54, v86
	v_cndmask_b32_e64 v86, v86, v43, s[50:51]
	v_cndmask_b32_e64 v54, v54, v126, s[50:51]
	v_sub_f32_e32 v43, v55, v87
	v_add_f32_e32 v126, v55, v87
	v_cndmask_b32_e64 v87, v87, v43, s[50:51]
	v_cndmask_b32_e64 v55, v55, v126, s[50:51]
	v_sub_f32_e32 v43, v56, v88
; __device__ __forceinline__ void phase_prep(const Params& P, int l, unsigned char* lds) {
;     ...
;             float* U = (float*)lds;
;             float* U2 = U + 64 * 256;
; #pragma unroll
;             for (int rep = 0; rep < 4; ++rep) {
;                 const int id = tid + 512 * rep, tok = id >> 5, ch = id & 31;
;                 const u32x4 w = *(const u32x4*)(proj + (size_t)(r0 + tok) * INW + PD_U + 8 * ch);
;                 f32x4 a0 = (f32x4){bflo(w.x), bfhi(w.x), bflo(w.y), bfhi(w.y)}, a1 = (f32x4){bflo(w.z), bfhi(w.z), bflo(w.w), bfhi(w.w)};
;                 float* d = U + tok * 256 + 8 * ch;
;                 if (!is_ctx) {
;                     const int tg = t0 - CTX + tok, mt = (tg == 0) ? SEQ / 2 : SEQ - tg;
;                     const u32x4 m = *(const u32x4*)(proj + ((size_t)b * TT + CTX + mt) * INW + PD_U + 8 * ch);
;                     const f32x4 m0 = (f32x4){bflo(m.x), bfhi(m.x), bflo(m.y), bfhi(m.y)}, m1 = (f32x4){bflo(m.z), bfhi(m.z), bflo(m.w), bfhi(m.w)};
;                     float* d2 = U2 + tok * 256 + 8 * ch;
;                     if (tg == 0) { *(f32x4*)d2 = m0; *(f32x4*)(d2 + 4) = m1; }
;                     else { *(f32x4*)d2 = a0 - m0; *(f32x4*)(d2 + 4) = a1 - m1; a0 = a0 + m0; a1 = a1 + m1; }
;                 }
;                 *(f32x4*)d = a0; *(f32x4*)(d + 4) = a1;
;             }
;             __syncthreads();
	v_add_f32_e32 v126, v56, v88
	v_cndmask_b32_e64 v88, v88, v43, s[50:51]
	v_cndmask_b32_e64 v56, v56, v126, s[50:51]
	v_sub_f32_e32 v43, v57, v89
	v_add_f32_e32 v126, v57, v89
	v_cndmask_b32_e64 v89, v89, v43, s[50:51]
	v_cndmask_b32_e64 v57, v57, v126, s[50:51]
	v_sub_f32_e32 v43, v58, v90
	v_add_f32_e32 v126, v58, v90
	v_cndmask_b32_e64 v90, v90, v43, s[50:51]
	v_cndmask_b32_e64 v58, v58, v126, s[50:51]
	v_sub_f32_e32 v43, v59, v91
	v_add_f32_e32 v126, v59, v91
	v_cndmask_b32_e64 v91, v91, v43, s[50:51]
	v_cndmask_b32_e64 v59, v59, v126, s[50:51]
	v_sub_f32_e32 v43, v60, v92
	v_add_f32_e32 v126, v60, v92
	v_cndmask_b32_e64 v92, v92, v43, s[50:51]
	v_cndmask_b32_e64 v60, v60, v126, s[50:51]
	v_sub_f32_e32 v43, v61, v93
	v_add_f32_e32 v126, v61, v93
	v_cndmask_b32_e64 v93, v93, v43, s[50:51]
	v_cndmask_b32_e64 v61, v61, v126, s[50:51]
	v_sub_f32_e32 v43, v62, v94
	v_add_f32_e32 v126, v62, v94
	v_cndmask_b32_e64 v94, v94, v43, s[50:51]
	v_cndmask_b32_e64 v62, v62, v126, s[50:51]
	v_sub_f32_e32 v43, v63, v95
	v_add_f32_e32 v126, v63, v95
	v_cndmask_b32_e64 v95, v95, v43, s[50:51]
	v_cndmask_b32_e64 v63, v63, v126, s[50:51]
	v_sub_f32_e32 v43, v64, v96
	v_add_f32_e32 v126, v64, v96
	v_cndmask_b32_e64 v96, v96, v43, s[50:51]
	v_cndmask_b32_e64 v64, v64, v126, s[50:51]
	v_sub_f32_e32 v43, v65, v97
	v_add_f32_e32 v126, v65, v97
	v_cndmask_b32_e64 v97, v97, v43, s[50:51]
	v_cndmask_b32_e64 v65, v65, v126, s[50:51]
	v_sub_f32_e32 v43, v66, v98
	v_add_f32_e32 v126, v66, v98
	v_cndmask_b32_e64 v98, v98, v43, s[50:51]
	v_cndmask_b32_e64 v66, v66, v126, s[50:51]
	v_sub_f32_e32 v43, v67, v99
	v_add_f32_e32 v126, v67, v99
	v_cndmask_b32_e64 v99, v99, v43, s[50:51]
	v_cndmask_b32_e64 v67, v67, v126, s[50:51]
	v_sub_f32_e32 v43, v68, v100
	v_add_f32_e32 v126, v68, v100
	v_cndmask_b32_e64 v100, v100, v43, s[50:51]
	v_cndmask_b32_e64 v68, v68, v126, s[50:51]
	v_sub_f32_e32 v43, v69, v101
	v_add_f32_e32 v126, v69, v101
	v_cndmask_b32_e64 v101, v101, v43, s[50:51]
	v_cndmask_b32_e64 v69, v69, v126, s[50:51]
	v_sub_f32_e32 v43, v70, v102
	v_add_f32_e32 v126, v70, v102
	v_cndmask_b32_e64 v102, v102, v43, s[50:51]
	v_cndmask_b32_e64 v70, v70, v126, s[50:51]
	v_sub_f32_e32 v43, v71, v103
	v_add_f32_e32 v126, v71, v103
	v_cndmask_b32_e64 v103, v103, v43, s[50:51]
	v_cndmask_b32_e64 v71, v71, v126, s[50:51]
	v_sub_f32_e32 v43, v72, v104
	v_add_f32_e32 v126, v72, v104
	v_cndmask_b32_e64 v104, v104, v43, s[50:51]
	v_cndmask_b32_e64 v72, v72, v126, s[50:51]
	v_sub_f32_e32 v43, v73, v105
	v_add_f32_e32 v126, v73, v105
	v_cndmask_b32_e64 v105, v105, v43, s[50:51]
	v_cndmask_b32_e64 v73, v73, v126, s[50:51]
	v_sub_f32_e32 v43, v74, v106
	v_add_f32_e32 v126, v74, v106
	v_cndmask_b32_e64 v106, v106, v43, s[50:51]
	v_cndmask_b32_e64 v74, v74, v126, s[50:51]
	v_sub_f32_e32 v43, v75, v107
	v_add_f32_e32 v126, v75, v107
	v_cndmask_b32_e64 v107, v107, v43, s[50:51]
	v_cndmask_b32_e64 v75, v75, v126, s[50:51]
	v_sub_f32_e32 v43, v76, v108
	v_add_f32_e32 v126, v76, v108
	v_cndmask_b32_e64 v108, v108, v43, s[50:51]
	v_cndmask_b32_e64 v76, v76, v126, s[50:51]
	ds_write_b32 v36, v77
	ds_write_b32 v36, v78 offset:256
	ds_write_b32 v36, v79 offset:512
	ds_write_b32 v36, v80 offset:768
	ds_write_b32 v36, v81 offset:1024
	ds_write_b32 v36, v82 offset:1280
	ds_write_b32 v36, v83 offset:1536
	ds_write_b32 v36, v84 offset:1792
	ds_write_b32 v36, v85 offset:2048
	ds_write_b32 v36, v86 offset:2304
	ds_write_b32 v36, v87 offset:2560
	ds_write_b32 v36, v88 offset:2816
	ds_write_b32 v36, v89 offset:3072
	ds_write_b32 v36, v90 offset:3328
	ds_write_b32 v36, v91 offset:3584
	ds_write_b32 v36, v92 offset:3840
	ds_write_b32 v36, v93 offset:4096
	ds_write_b32 v36, v94 offset:4352
	ds_write_b32 v36, v95 offset:4608
	ds_write_b32 v36, v96 offset:4864
	ds_write_b32 v36, v97 offset:5120
	ds_write_b32 v36, v98 offset:5376
	ds_write_b32 v36, v99 offset:5632
	ds_write_b32 v36, v100 offset:5888
	ds_write_b32 v36, v101 offset:6144
	ds_write_b32 v36, v102 offset:6400
	ds_write_b32 v36, v103 offset:6656
	ds_write_b32 v36, v104 offset:6912
	ds_write_b32 v36, v105 offset:7168
	ds_write_b32 v36, v106 offset:7424
	ds_write_b32 v36, v107 offset:7680
	ds_write_b32 v36, v108 offset:7936
.Ldft_wr_u:
	ds_write_b32 v35, v45
	ds_write_b32 v35, v46 offset:256
	ds_write_b32 v35, v47 offset:512
	ds_write_b32 v35, v48 offset:768
	ds_write_b32 v35, v49 offset:1024
	ds_write_b32 v35, v50 offset:1280
	ds_write_b32 v35, v51 offset:1536
	ds_write_b32 v35, v52 offset:1792
	ds_write_b32 v35, v53 offset:2048
	ds_write_b32 v35, v54 offset:2304
	ds_write_b32 v35, v55 offset:2560
	ds_write_b32 v35, v56 offset:2816
	ds_write_b32 v35, v57 offset:3072
	ds_write_b32 v35, v58 offset:3328
	ds_write_b32 v35, v59 offset:3584
	ds_write_b32 v35, v60 offset:3840
	ds_write_b32 v35, v61 offset:4096
	ds_write_b32 v35, v62 offset:4352
	ds_write_b32 v35, v63 offset:4608
	ds_write_b32 v35, v64 offset:4864
	ds_write_b32 v35, v65 offset:5120
	ds_write_b32 v35, v66 offset:5376
	ds_write_b32 v35, v67 offset:5632
	ds_write_b32 v35, v68 offset:5888
	ds_write_b32 v35, v69 offset:6144
	ds_write_b32 v35, v70 offset:6400
	ds_write_b32 v35, v71 offset:6656
	ds_write_b32 v35, v72 offset:6912
	ds_write_b32 v35, v73 offset:7168
	ds_write_b32 v35, v74 offset:7424
	ds_write_b32 v35, v75 offset:7680
	ds_write_b32 v35, v76 offset:7936
	s_waitcnt lgkmcnt(0)
	s_barrier
; __device__ __forceinline__ void phase_prep(const Params& P, int l, unsigned char* lds) {
;     ...
;             for (int c = 0; c < 64; ++c) {
;                 float cv[4], sv[4];
; #pragma unroll
;                 for (int q = 0; q < 4; ++q) { const float rev = (float)((c * (cp0 + q)) & 63) * (1.0f / 64.0f); cv[q] = __builtin_amdgcn_cosf(rev) * 0.125f; sv[q] = __builtin_amdgcn_sinf(rev) * 0.125f; }
; #pragma unroll
	v_add_u32_e32 v41, 32, v34
	v_mul_u32_u24_e32 v120, v33, v34
	v_mul_u32_u24_e32 v121, v33, v41
	v_lshlrev_b32_e32 v122, 1, v34
	v_lshlrev_b32_e32 v123, 1, v41
	v_and_b32_e32 v41, 63, v120
	v_cvt_f32_u32_e32 v41, v41
	v_mul_f32_e32 v41, 0x3c800000, v41
	v_cos_f32_e32 v42, v41
	v_sin_f32_e32 v43, v41
	v_add_u32_e32 v120, v120, v122
	v_mul_f32_e32 v130, 0x3e000000, v42
	v_mul_f32_e32 v194, 0x3e000000, v43
	v_and_b32_e32 v41, 63, v121
	v_cvt_f32_u32_e32 v41, v41
	v_mul_f32_e32 v41, 0x3c800000, v41
	v_cos_f32_e32 v42, v41
	v_sin_f32_e32 v43, v41
	v_add_u32_e32 v121, v121, v123
	v_mul_f32_e32 v162, 0x3e000000, v42
	v_mul_f32_e32 v230, 0x3e000000, v43
	v_and_b32_e32 v41, 63, v120
	v_cvt_f32_u32_e32 v41, v41
	v_mul_f32_e32 v41, 0x3c800000, v41
	v_cos_f32_e32 v42, v41
	v_sin_f32_e32 v43, v41
	v_add_u32_e32 v120, v120, v122
	v_mul_f32_e32 v131, 0x3e000000, v42
	v_mul_f32_e32 v195, 0x3e000000, v43
	v_and_b32_e32 v41, 63, v121
	v_cvt_f32_u32_e32 v41, v41
	v_mul_f32_e32 v41, 0x3c800000, v41
	v_cos_f32_e32 v42, v41
	v_sin_f32_e32 v43, v41
	v_add_u32_e32 v121, v121, v123
	v_mul_f32_e32 v163, 0x3e000000, v42
	v_mul_f32_e32 v231, 0x3e000000, v43
	v_and_b32_e32 v41, 63, v120
	v_cvt_f32_u32_e32 v41, v41
	v_mul_f32_e32 v41, 0x3c800000, v41
	v_cos_f32_e32 v42, v41
	v_sin_f32_e32 v43, v41
	v_add_u32_e32 v120, v120, v122
	v_mul_f32_e32 v132, 0x3e000000, v42
	v_mul_f32_e32 v196, 0x3e000000, v43
	v_and_b32_e32 v41, 63, v121
	v_cvt_f32_u32_e32 v41, v41
	v_mul_f32_e32 v41, 0x3c800000, v41
	v_cos_f32_e32 v42, v41
	v_sin_f32_e32 v43, v41
	v_add_u32_e32 v121, v121, v123
	v_mul_f32_e32 v164, 0x3e000000, v42
	v_mul_f32_e32 v232, 0x3e000000, v43
	v_and_b32_e32 v41, 63, v120
	v_cvt_f32_u32_e32 v41, v41
	v_mul_f32_e32 v41, 0x3c800000, v41
	v_cos_f32_e32 v42, v41
	v_sin_f32_e32 v43, v41
	v_add_u32_e32 v120, v120, v122
	v_mul_f32_e32 v133, 0x3e000000, v42
	v_mul_f32_e32 v197, 0x3e000000, v43
	v_and_b32_e32 v41, 63, v121
	v_cvt_f32_u32_e32 v41, v41
	v_mul_f32_e32 v41, 0x3c800000, v41
	v_cos_f32_e32 v42, v41
	v_sin_f32_e32 v43, v41
	v_add_u32_e32 v121, v121, v123
	v_mul_f32_e32 v165, 0x3e000000, v42
	v_mul_f32_e32 v233, 0x3e000000, v43
	v_and_b32_e32 v41, 63, v120
	v_cvt_f32_u32_e32 v41, v41
	v_mul_f32_e32 v41, 0x3c800000, v41
	v_cos_f32_e32 v42, v41
	v_sin_f32_e32 v43, v41
	v_add_u32_e32 v120, v120, v122
	v_mul_f32_e32 v134, 0x3e000000, v42
	v_mul_f32_e32 v198, 0x3e000000, v43
	v_and_b32_e32 v41, 63, v121
	v_cvt_f32_u32_e32 v41, v41
	v_mul_f32_e32 v41, 0x3c800000, v41
	v_cos_f32_e32 v42, v41
	v_sin_f32_e32 v43, v41
	v_add_u32_e32 v121, v121, v123
	v_mul_f32_e32 v166, 0x3e000000, v42
	v_mul_f32_e32 v234, 0x3e000000, v43
	v_and_b32_e32 v41, 63, v120
	v_cvt_f32_u32_e32 v41, v41
	v_mul_f32_e32 v41, 0x3c800000, v41
	v_cos_f32_e32 v42, v41
	v_sin_f32_e32 v43, v41
	v_add_u32_e32 v120, v120, v122
	v_mul_f32_e32 v135, 0x3e000000, v42
	v_mul_f32_e32 v199, 0x3e000000, v43
	v_and_b32_e32 v41, 63, v121
	v_cvt_f32_u32_e32 v41, v41
	v_mul_f32_e32 v41, 0x3c800000, v41
	v_cos_f32_e32 v42, v41
	v_sin_f32_e32 v43, v41
	v_add_u32_e32 v121, v121, v123
	v_mul_f32_e32 v167, 0x3e000000, v42
	v_mul_f32_e32 v235, 0x3e000000, v43
	v_and_b32_e32 v41, 63, v120
	v_cvt_f32_u32_e32 v41, v41
	v_mul_f32_e32 v41, 0x3c800000, v41
	v_cos_f32_e32 v42, v41
	v_sin_f32_e32 v43, v41
	v_add_u32_e32 v120, v120, v122
	v_mul_f32_e32 v136, 0x3e000000, v42
	v_mul_f32_e32 v204, 0x3e000000, v43
	v_and_b32_e32 v41, 63, v121
	v_cvt_f32_u32_e32 v41, v41
	v_mul_f32_e32 v41, 0x3c800000, v41
	v_cos_f32_e32 v42, v41
	v_sin_f32_e32 v43, v41
	v_add_u32_e32 v121, v121, v123
	v_mul_f32_e32 v168, 0x3e000000, v42
	v_mul_f32_e32 v236, 0x3e000000, v43
	v_and_b32_e32 v41, 63, v120
	v_cvt_f32_u32_e32 v41, v41
	v_mul_f32_e32 v41, 0x3c800000, v41
	v_cos_f32_e32 v42, v41
	v_sin_f32_e32 v43, v41
	v_add_u32_e32 v120, v120, v122
	v_mul_f32_e32 v137, 0x3e000000, v42
	v_mul_f32_e32 v205, 0x3e000000, v43
	v_and_b32_e32 v41, 63, v121
	v_cvt_f32_u32_e32 v41, v41
	v_mul_f32_e32 v41, 0x3c800000, v41
	v_cos_f32_e32 v42, v41
	v_sin_f32_e32 v43, v41
	v_add_u32_e32 v121, v121, v123
	v_mul_f32_e32 v169, 0x3e000000, v42
	v_mul_f32_e32 v237, 0x3e000000, v43
	v_and_b32_e32 v41, 63, v120
	v_cvt_f32_u32_e32 v41, v41
	v_mul_f32_e32 v41, 0x3c800000, v41
	v_cos_f32_e32 v42, v41
	v_sin_f32_e32 v43, v41
	v_add_u32_e32 v120, v120, v122
	v_mul_f32_e32 v138, 0x3e000000, v42
	v_mul_f32_e32 v206, 0x3e000000, v43
	v_and_b32_e32 v41, 63, v121
	v_cvt_f32_u32_e32 v41, v41
	v_mul_f32_e32 v41, 0x3c800000, v41
	v_cos_f32_e32 v42, v41
	v_sin_f32_e32 v43, v41
	v_add_u32_e32 v121, v121, v123
	v_mul_f32_e32 v170, 0x3e000000, v42
	v_mul_f32_e32 v238, 0x3e000000, v43
	v_and_b32_e32 v41, 63, v120
	v_cvt_f32_u32_e32 v41, v41
	v_mul_f32_e32 v41, 0x3c800000, v41
	v_cos_f32_e32 v42, v41
	v_sin_f32_e32 v43, v41
	v_add_u32_e32 v120, v120, v122
	v_mul_f32_e32 v139, 0x3e000000, v42
	v_mul_f32_e32 v207, 0x3e000000, v43
	v_and_b32_e32 v41, 63, v121
	v_cvt_f32_u32_e32 v41, v41
	v_mul_f32_e32 v41, 0x3c800000, v41
	v_cos_f32_e32 v42, v41
	v_sin_f32_e32 v43, v41
	v_add_u32_e32 v121, v121, v123
	v_mul_f32_e32 v171, 0x3e000000, v42
	v_mul_f32_e32 v239, 0x3e000000, v43
	v_and_b32_e32 v41, 63, v120
	v_cvt_f32_u32_e32 v41, v41
	v_mul_f32_e32 v41, 0x3c800000, v41
	v_cos_f32_e32 v42, v41
	v_sin_f32_e32 v43, v41
	v_add_u32_e32 v120, v120, v122
	v_mul_f32_e32 v140, 0x3e000000, v42
	v_mul_f32_e32 v208, 0x3e000000, v43
	v_and_b32_e32 v41, 63, v121
	v_cvt_f32_u32_e32 v41, v41
	v_mul_f32_e32 v41, 0x3c800000, v41
	v_cos_f32_e32 v42, v41
	v_sin_f32_e32 v43, v41
	v_add_u32_e32 v121, v121, v123
	v_mul_f32_e32 v172, 0x3e000000, v42
	v_mul_f32_e32 v240, 0x3e000000, v43
	v_and_b32_e32 v41, 63, v120
	v_cvt_f32_u32_e32 v41, v41
; __device__ __forceinline__ void phase_prep(const Params& P, int l, unsigned char* lds) {
;     ...
;                 for (int q = 0; q < 4; ++q) { const float rev = (float)((c * (cp0 + q)) & 63) * (1.0f / 64.0f); cv[q] = __builtin_amdgcn_cosf(rev) * 0.125f; sv[q] = __builtin_amdgcn_sinf(rev) * 0.125f; }
	v_mul_f32_e32 v41, 0x3c800000, v41
	v_cos_f32_e32 v42, v41
	v_sin_f32_e32 v43, v41
	v_add_u32_e32 v120, v120, v122
	v_mul_f32_e32 v141, 0x3e000000, v42
	v_mul_f32_e32 v209, 0x3e000000, v43
	v_and_b32_e32 v41, 63, v121
	v_cvt_f32_u32_e32 v41, v41
	v_mul_f32_e32 v41, 0x3c800000, v41
	v_cos_f32_e32 v42, v41
	v_sin_f32_e32 v43, v41
	v_add_u32_e32 v121, v121, v123
	v_mul_f32_e32 v173, 0x3e000000, v42
	v_mul_f32_e32 v241, 0x3e000000, v43
	v_and_b32_e32 v41, 63, v120
	v_cvt_f32_u32_e32 v41, v41
	v_mul_f32_e32 v41, 0x3c800000, v41
	v_cos_f32_e32 v42, v41
	v_sin_f32_e32 v43, v41
	v_add_u32_e32 v120, v120, v122
	v_mul_f32_e32 v142, 0x3e000000, v42
	v_mul_f32_e32 v210, 0x3e000000, v43
	v_and_b32_e32 v41, 63, v121
	v_cvt_f32_u32_e32 v41, v41
	v_mul_f32_e32 v41, 0x3c800000, v41
	v_cos_f32_e32 v42, v41
	v_sin_f32_e32 v43, v41
	v_add_u32_e32 v121, v121, v123
	v_mul_f32_e32 v174, 0x3e000000, v42
	v_mul_f32_e32 v243, 0x3e000000, v43
	v_and_b32_e32 v41, 63, v120
	v_cvt_f32_u32_e32 v41, v41
	v_mul_f32_e32 v41, 0x3c800000, v41
	v_cos_f32_e32 v42, v41
	v_sin_f32_e32 v43, v41
	v_add_u32_e32 v120, v120, v122
	v_mul_f32_e32 v143, 0x3e000000, v42
	v_mul_f32_e32 v211, 0x3e000000, v43
	v_and_b32_e32 v41, 63, v121
	v_cvt_f32_u32_e32 v41, v41
	v_mul_f32_e32 v41, 0x3c800000, v41
	v_cos_f32_e32 v42, v41
	v_sin_f32_e32 v43, v41
	v_add_u32_e32 v121, v121, v123
	v_mul_f32_e32 v175, 0x3e000000, v42
	v_mul_f32_e32 v244, 0x3e000000, v43
	v_and_b32_e32 v41, 63, v120
	v_cvt_f32_u32_e32 v41, v41
	v_mul_f32_e32 v41, 0x3c800000, v41
	v_cos_f32_e32 v42, v41
	v_sin_f32_e32 v43, v41
	v_add_u32_e32 v120, v120, v122
	v_mul_f32_e32 v144, 0x3e000000, v42
	v_mul_f32_e32 v212, 0x3e000000, v43
	v_and_b32_e32 v41, 63, v121
	v_cvt_f32_u32_e32 v41, v41
	v_mul_f32_e32 v41, 0x3c800000, v41
	v_cos_f32_e32 v42, v41
	v_sin_f32_e32 v43, v41
	v_add_u32_e32 v121, v121, v123
	v_mul_f32_e32 v176, 0x3e000000, v42
	v_mul_f32_e32 v245, 0x3e000000, v43
	v_and_b32_e32 v41, 63, v120
	v_cvt_f32_u32_e32 v41, v41
	v_mul_f32_e32 v41, 0x3c800000, v41
	v_cos_f32_e32 v42, v41
	v_sin_f32_e32 v43, v41
	v_add_u32_e32 v120, v120, v122
	v_mul_f32_e32 v145, 0x3e000000, v42
	v_mul_f32_e32 v213, 0x3e000000, v43
	v_and_b32_e32 v41, 63, v121
	v_cvt_f32_u32_e32 v41, v41
	v_mul_f32_e32 v41, 0x3c800000, v41
	v_cos_f32_e32 v42, v41
	v_sin_f32_e32 v43, v41
	v_add_u32_e32 v121, v121, v123
	v_mul_f32_e32 v177, 0x3e000000, v42
	v_mul_f32_e32 v246, 0x3e000000, v43
	v_and_b32_e32 v41, 63, v120
	v_cvt_f32_u32_e32 v41, v41
	v_mul_f32_e32 v41, 0x3c800000, v41
	v_cos_f32_e32 v42, v41
	v_sin_f32_e32 v43, v41
	v_add_u32_e32 v120, v120, v122
	v_mul_f32_e32 v146, 0x3e000000, v42
	v_mul_f32_e32 v214, 0x3e000000, v43
	v_and_b32_e32 v41, 63, v121
	v_cvt_f32_u32_e32 v41, v41
	v_mul_f32_e32 v41, 0x3c800000, v41
	v_cos_f32_e32 v42, v41
	v_sin_f32_e32 v43, v41
	v_add_u32_e32 v121, v121, v123
	v_mul_f32_e32 v178, 0x3e000000, v42
	v_mul_f32_e32 v247, 0x3e000000, v43
	v_and_b32_e32 v41, 63, v120
	v_cvt_f32_u32_e32 v41, v41
	v_mul_f32_e32 v41, 0x3c800000, v41
	v_cos_f32_e32 v42, v41
	v_sin_f32_e32 v43, v41
	v_add_u32_e32 v120, v120, v122
	v_mul_f32_e32 v147, 0x3e000000, v42
	v_mul_f32_e32 v215, 0x3e000000, v43
	v_and_b32_e32 v41, 63, v121
	v_cvt_f32_u32_e32 v41, v41
	v_mul_f32_e32 v41, 0x3c800000, v41
	v_cos_f32_e32 v42, v41
	v_sin_f32_e32 v43, v41
	v_add_u32_e32 v121, v121, v123
	v_mul_f32_e32 v179, 0x3e000000, v42
	v_mul_f32_e32 v248, 0x3e000000, v43
	v_and_b32_e32 v41, 63, v120
	v_cvt_f32_u32_e32 v41, v41
	v_mul_f32_e32 v41, 0x3c800000, v41
	v_cos_f32_e32 v42, v41
	v_sin_f32_e32 v43, v41
	v_add_u32_e32 v120, v120, v122
	v_mul_f32_e32 v148, 0x3e000000, v42
	v_mul_f32_e32 v216, 0x3e000000, v43
	v_and_b32_e32 v41, 63, v121
	v_cvt_f32_u32_e32 v41, v41
	v_mul_f32_e32 v41, 0x3c800000, v41
	v_cos_f32_e32 v42, v41
	v_sin_f32_e32 v43, v41
	v_add_u32_e32 v121, v121, v123
	v_mul_f32_e32 v180, 0x3e000000, v42
	v_mul_f32_e32 v249, 0x3e000000, v43
	v_and_b32_e32 v41, 63, v120
	v_cvt_f32_u32_e32 v41, v41
	v_mul_f32_e32 v41, 0x3c800000, v41
	v_cos_f32_e32 v42, v41
	v_sin_f32_e32 v43, v41
	v_add_u32_e32 v120, v120, v122
	v_mul_f32_e32 v149, 0x3e000000, v42
	v_mul_f32_e32 v217, 0x3e000000, v43
	v_and_b32_e32 v41, 63, v121
	v_cvt_f32_u32_e32 v41, v41
	v_mul_f32_e32 v41, 0x3c800000, v41
	v_cos_f32_e32 v42, v41
	v_sin_f32_e32 v43, v41
	v_add_u32_e32 v121, v121, v123
	v_mul_f32_e32 v181, 0x3e000000, v42
	v_mul_f32_e32 v250, 0x3e000000, v43
	v_and_b32_e32 v41, 63, v120
	v_cvt_f32_u32_e32 v41, v41
	v_mul_f32_e32 v41, 0x3c800000, v41
	v_cos_f32_e32 v42, v41
	v_sin_f32_e32 v43, v41
	v_add_u32_e32 v120, v120, v122
	v_mul_f32_e32 v150, 0x3e000000, v42
	v_mul_f32_e32 v218, 0x3e000000, v43
	v_and_b32_e32 v41, 63, v121
	v_cvt_f32_u32_e32 v41, v41
	v_mul_f32_e32 v41, 0x3c800000, v41
	v_cos_f32_e32 v42, v41
	v_sin_f32_e32 v43, v41
	v_add_u32_e32 v121, v121, v123
	v_mul_f32_e32 v182, 0x3e000000, v42
	v_mul_f32_e32 v251, 0x3e000000, v43
	v_and_b32_e32 v41, 63, v120
	v_cvt_f32_u32_e32 v41, v41
	v_mul_f32_e32 v41, 0x3c800000, v41
	v_cos_f32_e32 v42, v41
	v_sin_f32_e32 v43, v41
	v_add_u32_e32 v120, v120, v122
	v_mul_f32_e32 v151, 0x3e000000, v42
	v_mul_f32_e32 v219, 0x3e000000, v43
	v_and_b32_e32 v41, 63, v121
	v_cvt_f32_u32_e32 v41, v41
	v_mul_f32_e32 v41, 0x3c800000, v41
	v_cos_f32_e32 v42, v41
	v_sin_f32_e32 v43, v41
	v_add_u32_e32 v121, v121, v123
	v_mul_f32_e32 v183, 0x3e000000, v42
	v_mul_f32_e32 v252, 0x3e000000, v43
	v_and_b32_e32 v41, 63, v120
	v_cvt_f32_u32_e32 v41, v41
	v_mul_f32_e32 v41, 0x3c800000, v41
	v_cos_f32_e32 v42, v41
	v_sin_f32_e32 v43, v41
	v_add_u32_e32 v120, v120, v122
	v_mul_f32_e32 v152, 0x3e000000, v42
	v_mul_f32_e32 v220, 0x3e000000, v43
	v_and_b32_e32 v41, 63, v121
; __device__ __forceinline__ void phase_prep(const Params& P, int l, unsigned char* lds) {
;     ...
;             const float* ub = U + t8 * 256 + g * 64;
;             const float* ub2 = is_ctx ? ub : ub + 64 * 256;
; #pragma unroll 2
;             for (int c = 0; c < 64; ++c) {
;                 float cv[4], sv[4];
; #pragma unroll
;                 for (int q = 0; q < 4; ++q) { const float rev = (float)((c * (cp0 + q)) & 63) * (1.0f / 64.0f); cv[q] = __builtin_amdgcn_cosf(rev) * 0.125f; sv[q] = __builtin_amdgcn_sinf(rev) * 0.125f; }
; #pragma unroll
	v_cvt_f32_u32_e32 v41, v41
	v_mul_f32_e32 v41, 0x3c800000, v41
	v_cos_f32_e32 v42, v41
	v_sin_f32_e32 v43, v41
	v_add_u32_e32 v121, v121, v123
	v_mul_f32_e32 v184, 0x3e000000, v42
	v_mul_f32_e32 v110, 0x3e000000, v43
	v_and_b32_e32 v41, 63, v120
	v_cvt_f32_u32_e32 v41, v41
	v_mul_f32_e32 v41, 0x3c800000, v41
	v_cos_f32_e32 v42, v41
	v_sin_f32_e32 v43, v41
	v_add_u32_e32 v120, v120, v122
	v_mul_f32_e32 v153, 0x3e000000, v42
	v_mul_f32_e32 v221, 0x3e000000, v43
	v_and_b32_e32 v41, 63, v121
	v_cvt_f32_u32_e32 v41, v41
	v_mul_f32_e32 v41, 0x3c800000, v41
	v_cos_f32_e32 v42, v41
	v_sin_f32_e32 v43, v41
	v_add_u32_e32 v121, v121, v123
	v_mul_f32_e32 v185, 0x3e000000, v42
	v_mul_f32_e32 v111, 0x3e000000, v43
	v_and_b32_e32 v41, 63, v120
	v_cvt_f32_u32_e32 v41, v41
	v_mul_f32_e32 v41, 0x3c800000, v41
	v_cos_f32_e32 v42, v41
	v_sin_f32_e32 v43, v41
	v_add_u32_e32 v120, v120, v122
	v_mul_f32_e32 v154, 0x3e000000, v42
	v_mul_f32_e32 v222, 0x3e000000, v43
	v_and_b32_e32 v41, 63, v121
	v_cvt_f32_u32_e32 v41, v41
	v_mul_f32_e32 v41, 0x3c800000, v41
	v_cos_f32_e32 v42, v41
	v_sin_f32_e32 v43, v41
	v_add_u32_e32 v121, v121, v123
	v_mul_f32_e32 v186, 0x3e000000, v42
	v_mul_f32_e32 v112, 0x3e000000, v43
	v_and_b32_e32 v41, 63, v120
	v_cvt_f32_u32_e32 v41, v41
	v_mul_f32_e32 v41, 0x3c800000, v41
	v_cos_f32_e32 v42, v41
	v_sin_f32_e32 v43, v41
	v_add_u32_e32 v120, v120, v122
	v_mul_f32_e32 v155, 0x3e000000, v42
	v_mul_f32_e32 v223, 0x3e000000, v43
	v_and_b32_e32 v41, 63, v121
	v_cvt_f32_u32_e32 v41, v41
	v_mul_f32_e32 v41, 0x3c800000, v41
	v_cos_f32_e32 v42, v41
	v_sin_f32_e32 v43, v41
	v_add_u32_e32 v121, v121, v123
	v_mul_f32_e32 v187, 0x3e000000, v42
	v_mul_f32_e32 v113, 0x3e000000, v43
	v_and_b32_e32 v41, 63, v120
	v_cvt_f32_u32_e32 v41, v41
	v_mul_f32_e32 v41, 0x3c800000, v41
	v_cos_f32_e32 v42, v41
	v_sin_f32_e32 v43, v41
	v_add_u32_e32 v120, v120, v122
	v_mul_f32_e32 v156, 0x3e000000, v42
	v_mul_f32_e32 v224, 0x3e000000, v43
	v_and_b32_e32 v41, 63, v121
	v_cvt_f32_u32_e32 v41, v41
	v_mul_f32_e32 v41, 0x3c800000, v41
	v_cos_f32_e32 v42, v41
	v_sin_f32_e32 v43, v41
	v_add_u32_e32 v121, v121, v123
	v_mul_f32_e32 v188, 0x3e000000, v42
	v_mul_f32_e32 v114, 0x3e000000, v43
	v_and_b32_e32 v41, 63, v120
	v_cvt_f32_u32_e32 v41, v41
	v_mul_f32_e32 v41, 0x3c800000, v41
	v_cos_f32_e32 v42, v41
	v_sin_f32_e32 v43, v41
	v_add_u32_e32 v120, v120, v122
	v_mul_f32_e32 v157, 0x3e000000, v42
	v_mul_f32_e32 v225, 0x3e000000, v43
	v_and_b32_e32 v41, 63, v121
	v_cvt_f32_u32_e32 v41, v41
	v_mul_f32_e32 v41, 0x3c800000, v41
	v_cos_f32_e32 v42, v41
	v_sin_f32_e32 v43, v41
	v_add_u32_e32 v121, v121, v123
	v_mul_f32_e32 v189, 0x3e000000, v42
	v_mul_f32_e32 v115, 0x3e000000, v43
	v_and_b32_e32 v41, 63, v120
	v_cvt_f32_u32_e32 v41, v41
	v_mul_f32_e32 v41, 0x3c800000, v41
	v_cos_f32_e32 v42, v41
	v_sin_f32_e32 v43, v41
	v_add_u32_e32 v120, v120, v122
	v_mul_f32_e32 v158, 0x3e000000, v42
	v_mul_f32_e32 v226, 0x3e000000, v43
	v_and_b32_e32 v41, 63, v121
	v_cvt_f32_u32_e32 v41, v41
	v_mul_f32_e32 v41, 0x3c800000, v41
	v_cos_f32_e32 v42, v41
	v_sin_f32_e32 v43, v41
	v_add_u32_e32 v121, v121, v123
	v_mul_f32_e32 v190, 0x3e000000, v42
	v_mul_f32_e32 v116, 0x3e000000, v43
	v_and_b32_e32 v41, 63, v120
	v_cvt_f32_u32_e32 v41, v41
	v_mul_f32_e32 v41, 0x3c800000, v41
	v_cos_f32_e32 v42, v41
	v_sin_f32_e32 v43, v41
	v_add_u32_e32 v120, v120, v122
	v_mul_f32_e32 v159, 0x3e000000, v42
	v_mul_f32_e32 v227, 0x3e000000, v43
	v_and_b32_e32 v41, 63, v121
	v_cvt_f32_u32_e32 v41, v41
	v_mul_f32_e32 v41, 0x3c800000, v41
	v_cos_f32_e32 v42, v41
	v_sin_f32_e32 v43, v41
	v_add_u32_e32 v121, v121, v123
	v_mul_f32_e32 v191, 0x3e000000, v42
	v_mul_f32_e32 v117, 0x3e000000, v43
	v_and_b32_e32 v41, 63, v120
	v_cvt_f32_u32_e32 v41, v41
	v_mul_f32_e32 v41, 0x3c800000, v41
	v_cos_f32_e32 v42, v41
	v_sin_f32_e32 v43, v41
	v_add_u32_e32 v120, v120, v122
	v_mul_f32_e32 v160, 0x3e000000, v42
	v_mul_f32_e32 v228, 0x3e000000, v43
	v_and_b32_e32 v41, 63, v121
	v_cvt_f32_u32_e32 v41, v41
	v_mul_f32_e32 v41, 0x3c800000, v41
	v_cos_f32_e32 v42, v41
	v_sin_f32_e32 v43, v41
	v_add_u32_e32 v121, v121, v123
	v_mul_f32_e32 v192, 0x3e000000, v42
	v_mul_f32_e32 v118, 0x3e000000, v43
	v_and_b32_e32 v41, 63, v120
	v_cvt_f32_u32_e32 v41, v41
	v_mul_f32_e32 v41, 0x3c800000, v41
	v_cos_f32_e32 v42, v41
	v_sin_f32_e32 v43, v41
	v_add_u32_e32 v120, v120, v122
	v_mul_f32_e32 v161, 0x3e000000, v42
	v_mul_f32_e32 v229, 0x3e000000, v43
	v_and_b32_e32 v41, 63, v121
	v_cvt_f32_u32_e32 v41, v41
	v_mul_f32_e32 v41, 0x3c800000, v41
	v_cos_f32_e32 v42, v41
	v_sin_f32_e32 v43, v41
	v_add_u32_e32 v121, v121, v123
	v_mul_f32_e32 v193, 0x3e000000, v42
	v_mul_f32_e32 v119, 0x3e000000, v43
	s_lshl_b32 s7, s15, 14
	s_lshl_b32 s18, s13, 7
	s_add_u32 s7, s7, s18
	v_lshlrev_b32_e32 v35, 8, v33
	v_lshl_add_u32 v35, v34, 2, v35
	v_add_u32_e32 v35, s7, v35
	v_add_u32_e32 v36, 0x10000, v35
	s_and_b64 vcc, exec, s[42:43]
	s_cbranch_vccnz .Ldft_lat_a
	v_mov_b32_e32 v36, v35
; __device__ __forceinline__ void phase_prep(const Params& P, int l, unsigned char* lds) {
;     ...
; #pragma unroll 2
;             for (int c = 0; c < 64; ++c) {
;                 float cv[4], sv[4];
; #pragma unroll
;                 for (int q = 0; q < 4; ++q) { const float rev = (float)((c * (cp0 + q)) & 63) * (1.0f / 64.0f); cv[q] = __builtin_amdgcn_cosf(rev) * 0.125f; sv[q] = __builtin_amdgcn_sinf(rev) * 0.125f; }
; #pragma unroll
;                 for (int t = 0; t < 8; ++t) { const float u = ub[t * 256 + c], u2 = ub2[t * 256 + c];
; #pragma unroll
;                     for (int q = 0; q < 4; ++q) { aC[q][t] += u * cv[q]; aS[q][t] += u2 * ((t == 0 && sp0) ? cv[q] : sv[q]); } }
;             }
.Ldft_lat_a:
	ds_read_b32 v37, v35
	ds_read_b32 v38, v36
	ds_read_b32 v39, v35 offset:512
	ds_read_b32 v40, v36 offset:512
	s_waitcnt lgkmcnt(2)
	v_mfma_f32_32x32x2_f32 v[0:15], v37, v130, 0
	v_mfma_f32_32x32x2_f32 v[16:31], v37, v162, 0
	v_mfma_f32_32x32x2_f32 v[46:61], v38, v194, 0
	v_mfma_f32_32x32x2_f32 v[62:77], v38, v230, 0
	ds_read_b32 v37, v35 offset:1024
	ds_read_b32 v38, v36 offset:1024
	s_waitcnt lgkmcnt(2)
	v_mfma_f32_32x32x2_f32 v[0:15], v39, v131, v[0:15]
	v_mfma_f32_32x32x2_f32 v[16:31], v39, v163, v[16:31]
	v_mfma_f32_32x32x2_f32 v[46:61], v40, v195, v[46:61]
	v_mfma_f32_32x32x2_f32 v[62:77], v40, v231, v[62:77]
	ds_read_b32 v39, v35 offset:1536
	ds_read_b32 v40, v36 offset:1536
	s_waitcnt lgkmcnt(2)
	v_mfma_f32_32x32x2_f32 v[0:15], v37, v132, v[0:15]
	v_mfma_f32_32x32x2_f32 v[16:31], v37, v164, v[16:31]
	v_mfma_f32_32x32x2_f32 v[46:61], v38, v196, v[46:61]
	v_mfma_f32_32x32x2_f32 v[62:77], v38, v232, v[62:77]
	ds_read_b32 v37, v35 offset:2048
	ds_read_b32 v38, v36 offset:2048
	s_waitcnt lgkmcnt(2)
	v_mfma_f32_32x32x2_f32 v[0:15], v39, v133, v[0:15]
	v_mfma_f32_32x32x2_f32 v[16:31], v39, v165, v[16:31]
	v_mfma_f32_32x32x2_f32 v[46:61], v40, v197, v[46:61]
	v_mfma_f32_32x32x2_f32 v[62:77], v40, v233, v[62:77]
	ds_read_b32 v39, v35 offset:2560
	ds_read_b32 v40, v36 offset:2560
	s_waitcnt lgkmcnt(2)
	v_mfma_f32_32x32x2_f32 v[0:15], v37, v134, v[0:15]
	v_mfma_f32_32x32x2_f32 v[16:31], v37, v166, v[16:31]
	v_mfma_f32_32x32x2_f32 v[46:61], v38, v198, v[46:61]
	v_mfma_f32_32x32x2_f32 v[62:77], v38, v234, v[62:77]
	ds_read_b32 v37, v35 offset:3072
	ds_read_b32 v38, v36 offset:3072
	s_waitcnt lgkmcnt(2)
	v_mfma_f32_32x32x2_f32 v[0:15], v39, v135, v[0:15]
	v_mfma_f32_32x32x2_f32 v[16:31], v39, v167, v[16:31]
	v_mfma_f32_32x32x2_f32 v[46:61], v40, v199, v[46:61]
	v_mfma_f32_32x32x2_f32 v[62:77], v40, v235, v[62:77]
	ds_read_b32 v39, v35 offset:3584
	ds_read_b32 v40, v36 offset:3584
	s_waitcnt lgkmcnt(2)
	v_mfma_f32_32x32x2_f32 v[0:15], v37, v136, v[0:15]
	v_mfma_f32_32x32x2_f32 v[16:31], v37, v168, v[16:31]
	v_mfma_f32_32x32x2_f32 v[46:61], v38, v204, v[46:61]
	v_mfma_f32_32x32x2_f32 v[62:77], v38, v236, v[62:77]
	ds_read_b32 v37, v35 offset:4096
	ds_read_b32 v38, v36 offset:4096
	s_waitcnt lgkmcnt(2)
	v_mfma_f32_32x32x2_f32 v[0:15], v39, v137, v[0:15]
	v_mfma_f32_32x32x2_f32 v[16:31], v39, v169, v[16:31]
	v_mfma_f32_32x32x2_f32 v[46:61], v40, v205, v[46:61]
	v_mfma_f32_32x32x2_f32 v[62:77], v40, v237, v[62:77]
	ds_read_b32 v39, v35 offset:4608
	ds_read_b32 v40, v36 offset:4608
	s_waitcnt lgkmcnt(2)
	v_mfma_f32_32x32x2_f32 v[0:15], v37, v138, v[0:15]
	v_mfma_f32_32x32x2_f32 v[16:31], v37, v170, v[16:31]
	v_mfma_f32_32x32x2_f32 v[46:61], v38, v206, v[46:61]
	v_mfma_f32_32x32x2_f32 v[62:77], v38, v238, v[62:77]
	ds_read_b32 v37, v35 offset:5120
	ds_read_b32 v38, v36 offset:5120
	s_waitcnt lgkmcnt(2)
	v_mfma_f32_32x32x2_f32 v[0:15], v39, v139, v[0:15]
	v_mfma_f32_32x32x2_f32 v[16:31], v39, v171, v[16:31]
	v_mfma_f32_32x32x2_f32 v[46:61], v40, v207, v[46:61]
	v_mfma_f32_32x32x2_f32 v[62:77], v40, v239, v[62:77]
	ds_read_b32 v39, v35 offset:5632
	ds_read_b32 v40, v36 offset:5632
	s_waitcnt lgkmcnt(2)
	v_mfma_f32_32x32x2_f32 v[0:15], v37, v140, v[0:15]
	v_mfma_f32_32x32x2_f32 v[16:31], v37, v172, v[16:31]
	v_mfma_f32_32x32x2_f32 v[46:61], v38, v208, v[46:61]
	v_mfma_f32_32x32x2_f32 v[62:77], v38, v240, v[62:77]
	ds_read_b32 v37, v35 offset:6144
	ds_read_b32 v38, v36 offset:6144
	s_waitcnt lgkmcnt(2)
	v_mfma_f32_32x32x2_f32 v[0:15], v39, v141, v[0:15]
	v_mfma_f32_32x32x2_f32 v[16:31], v39, v173, v[16:31]
	v_mfma_f32_32x32x2_f32 v[46:61], v40, v209, v[46:61]
	v_mfma_f32_32x32x2_f32 v[62:77], v40, v241, v[62:77]
	ds_read_b32 v39, v35 offset:6656
	ds_read_b32 v40, v36 offset:6656
	s_waitcnt lgkmcnt(2)
	v_mfma_f32_32x32x2_f32 v[0:15], v37, v142, v[0:15]
	v_mfma_f32_32x32x2_f32 v[16:31], v37, v174, v[16:31]
	v_mfma_f32_32x32x2_f32 v[46:61], v38, v210, v[46:61]
	v_mfma_f32_32x32x2_f32 v[62:77], v38, v243, v[62:77]
	ds_read_b32 v37, v35 offset:7168
	ds_read_b32 v38, v36 offset:7168
	s_waitcnt lgkmcnt(2)
	v_mfma_f32_32x32x2_f32 v[0:15], v39, v143, v[0:15]
	v_mfma_f32_32x32x2_f32 v[16:31], v39, v175, v[16:31]
	v_mfma_f32_32x32x2_f32 v[46:61], v40, v211, v[46:61]
	v_mfma_f32_32x32x2_f32 v[62:77], v40, v244, v[62:77]
	ds_read_b32 v39, v35 offset:7680
	ds_read_b32 v40, v36 offset:7680
	s_waitcnt lgkmcnt(2)
	v_mfma_f32_32x32x2_f32 v[0:15], v37, v144, v[0:15]
	v_mfma_f32_32x32x2_f32 v[16:31], v37, v176, v[16:31]
	v_mfma_f32_32x32x2_f32 v[46:61], v38, v212, v[46:61]
	v_mfma_f32_32x32x2_f32 v[62:77], v38, v245, v[62:77]
	ds_read_b32 v37, v35 offset:8192
	ds_read_b32 v38, v36 offset:8192
	s_waitcnt lgkmcnt(2)
	v_mfma_f32_32x32x2_f32 v[0:15], v39, v145, v[0:15]
	v_mfma_f32_32x32x2_f32 v[16:31], v39, v177, v[16:31]
	v_mfma_f32_32x32x2_f32 v[46:61], v40, v213, v[46:61]
	v_mfma_f32_32x32x2_f32 v[62:77], v40, v246, v[62:77]
	ds_read_b32 v39, v35 offset:8704
	ds_read_b32 v40, v36 offset:8704
	s_waitcnt lgkmcnt(2)
	v_mfma_f32_32x32x2_f32 v[0:15], v37, v146, v[0:15]
	v_mfma_f32_32x32x2_f32 v[16:31], v37, v178, v[16:31]
	v_mfma_f32_32x32x2_f32 v[46:61], v38, v214, v[46:61]
	v_mfma_f32_32x32x2_f32 v[62:77], v38, v247, v[62:77]
	ds_read_b32 v37, v35 offset:9216
	ds_read_b32 v38, v36 offset:9216
	s_waitcnt lgkmcnt(2)
	v_mfma_f32_32x32x2_f32 v[0:15], v39, v147, v[0:15]
	v_mfma_f32_32x32x2_f32 v[16:31], v39, v179, v[16:31]
	v_mfma_f32_32x32x2_f32 v[46:61], v40, v215, v[46:61]
	v_mfma_f32_32x32x2_f32 v[62:77], v40, v248, v[62:77]
	ds_read_b32 v39, v35 offset:9728
	ds_read_b32 v40, v36 offset:9728
	s_waitcnt lgkmcnt(2)
; __device__ __forceinline__ void phase_prep(const Params& P, int l, unsigned char* lds) {
;     ...
; #pragma unroll 2
;             for (int c = 0; c < 64; ++c) {
;                 float cv[4], sv[4];
; #pragma unroll
;                 for (int q = 0; q < 4; ++q) { const float rev = (float)((c * (cp0 + q)) & 63) * (1.0f / 64.0f); cv[q] = __builtin_amdgcn_cosf(rev) * 0.125f; sv[q] = __builtin_amdgcn_sinf(rev) * 0.125f; }
; #pragma unroll
;                 for (int t = 0; t < 8; ++t) { const float u = ub[t * 256 + c], u2 = ub2[t * 256 + c];
; #pragma unroll
;                     for (int q = 0; q < 4; ++q) { aC[q][t] += u * cv[q]; aS[q][t] += u2 * ((t == 0 && sp0) ? cv[q] : sv[q]); } }
;             }
	v_mfma_f32_32x32x2_f32 v[0:15], v37, v148, v[0:15]
	v_mfma_f32_32x32x2_f32 v[16:31], v37, v180, v[16:31]
	v_mfma_f32_32x32x2_f32 v[46:61], v38, v216, v[46:61]
	v_mfma_f32_32x32x2_f32 v[62:77], v38, v249, v[62:77]
	ds_read_b32 v37, v35 offset:10240
	ds_read_b32 v38, v36 offset:10240
	s_waitcnt lgkmcnt(2)
	v_mfma_f32_32x32x2_f32 v[0:15], v39, v149, v[0:15]
	v_mfma_f32_32x32x2_f32 v[16:31], v39, v181, v[16:31]
	v_mfma_f32_32x32x2_f32 v[46:61], v40, v217, v[46:61]
	v_mfma_f32_32x32x2_f32 v[62:77], v40, v250, v[62:77]
	ds_read_b32 v39, v35 offset:10752
	ds_read_b32 v40, v36 offset:10752
	s_waitcnt lgkmcnt(2)
	v_mfma_f32_32x32x2_f32 v[0:15], v37, v150, v[0:15]
	v_mfma_f32_32x32x2_f32 v[16:31], v37, v182, v[16:31]
	v_mfma_f32_32x32x2_f32 v[46:61], v38, v218, v[46:61]
	v_mfma_f32_32x32x2_f32 v[62:77], v38, v251, v[62:77]
	ds_read_b32 v37, v35 offset:11264
	ds_read_b32 v38, v36 offset:11264
	s_waitcnt lgkmcnt(2)
	v_mfma_f32_32x32x2_f32 v[0:15], v39, v151, v[0:15]
	v_mfma_f32_32x32x2_f32 v[16:31], v39, v183, v[16:31]
	v_mfma_f32_32x32x2_f32 v[46:61], v40, v219, v[46:61]
	v_mfma_f32_32x32x2_f32 v[62:77], v40, v252, v[62:77]
	ds_read_b32 v39, v35 offset:11776
	ds_read_b32 v40, v36 offset:11776
	s_waitcnt lgkmcnt(2)
	v_mfma_f32_32x32x2_f32 v[0:15], v37, v152, v[0:15]
	v_mfma_f32_32x32x2_f32 v[16:31], v37, v184, v[16:31]
	v_mfma_f32_32x32x2_f32 v[46:61], v38, v220, v[46:61]
	v_mfma_f32_32x32x2_f32 v[62:77], v38, v110, v[62:77]
	ds_read_b32 v37, v35 offset:12288
	ds_read_b32 v38, v36 offset:12288
	s_waitcnt lgkmcnt(2)
	v_mfma_f32_32x32x2_f32 v[0:15], v39, v153, v[0:15]
	v_mfma_f32_32x32x2_f32 v[16:31], v39, v185, v[16:31]
	v_mfma_f32_32x32x2_f32 v[46:61], v40, v221, v[46:61]
	v_mfma_f32_32x32x2_f32 v[62:77], v40, v111, v[62:77]
	ds_read_b32 v39, v35 offset:12800
	ds_read_b32 v40, v36 offset:12800
	s_waitcnt lgkmcnt(2)
	v_mfma_f32_32x32x2_f32 v[0:15], v37, v154, v[0:15]
	v_mfma_f32_32x32x2_f32 v[16:31], v37, v186, v[16:31]
	v_mfma_f32_32x32x2_f32 v[46:61], v38, v222, v[46:61]
	v_mfma_f32_32x32x2_f32 v[62:77], v38, v112, v[62:77]
	ds_read_b32 v37, v35 offset:13312
	ds_read_b32 v38, v36 offset:13312
	s_waitcnt lgkmcnt(2)
	v_mfma_f32_32x32x2_f32 v[0:15], v39, v155, v[0:15]
	v_mfma_f32_32x32x2_f32 v[16:31], v39, v187, v[16:31]
	v_mfma_f32_32x32x2_f32 v[46:61], v40, v223, v[46:61]
	v_mfma_f32_32x32x2_f32 v[62:77], v40, v113, v[62:77]
	ds_read_b32 v39, v35 offset:13824
	ds_read_b32 v40, v36 offset:13824
	s_waitcnt lgkmcnt(2)
	v_mfma_f32_32x32x2_f32 v[0:15], v37, v156, v[0:15]
	v_mfma_f32_32x32x2_f32 v[16:31], v37, v188, v[16:31]
	v_mfma_f32_32x32x2_f32 v[46:61], v38, v224, v[46:61]
	v_mfma_f32_32x32x2_f32 v[62:77], v38, v114, v[62:77]
	ds_read_b32 v37, v35 offset:14336
	ds_read_b32 v38, v36 offset:14336
	s_waitcnt lgkmcnt(2)
	v_mfma_f32_32x32x2_f32 v[0:15], v39, v157, v[0:15]
	v_mfma_f32_32x32x2_f32 v[16:31], v39, v189, v[16:31]
	v_mfma_f32_32x32x2_f32 v[46:61], v40, v225, v[46:61]
	v_mfma_f32_32x32x2_f32 v[62:77], v40, v115, v[62:77]
	ds_read_b32 v39, v35 offset:14848
	ds_read_b32 v40, v36 offset:14848
	s_waitcnt lgkmcnt(2)
	v_mfma_f32_32x32x2_f32 v[0:15], v37, v158, v[0:15]
	v_mfma_f32_32x32x2_f32 v[16:31], v37, v190, v[16:31]
	v_mfma_f32_32x32x2_f32 v[46:61], v38, v226, v[46:61]
	v_mfma_f32_32x32x2_f32 v[62:77], v38, v116, v[62:77]
	ds_read_b32 v37, v35 offset:15360
	ds_read_b32 v38, v36 offset:15360
	s_waitcnt lgkmcnt(2)
	v_mfma_f32_32x32x2_f32 v[0:15], v39, v159, v[0:15]
	v_mfma_f32_32x32x2_f32 v[16:31], v39, v191, v[16:31]
	v_mfma_f32_32x32x2_f32 v[46:61], v40, v227, v[46:61]
	v_mfma_f32_32x32x2_f32 v[62:77], v40, v117, v[62:77]
	ds_read_b32 v39, v35 offset:15872
	ds_read_b32 v40, v36 offset:15872
	s_waitcnt lgkmcnt(2)
	v_mfma_f32_32x32x2_f32 v[0:15], v37, v160, v[0:15]
	v_mfma_f32_32x32x2_f32 v[16:31], v37, v192, v[16:31]
	v_mfma_f32_32x32x2_f32 v[46:61], v38, v228, v[46:61]
	v_mfma_f32_32x32x2_f32 v[62:77], v38, v118, v[62:77]
	s_waitcnt lgkmcnt(0)
	v_mfma_f32_32x32x2_f32 v[0:15], v39, v161, v[0:15]
	v_mfma_f32_32x32x2_f32 v[16:31], v39, v193, v[16:31]
	v_mfma_f32_32x32x2_f32 v[46:61], v40, v229, v[46:61]
	v_mfma_f32_32x32x2_f32 v[62:77], v40, v119, v[62:77]
	s_cmp_eq_u32 s64, 0x100
	s_cbranch_scc0 .Ldft_nosp
	s_cmp_eq_u32 s13, 0
	s_cbranch_scc0 .Ldft_nosp
	ds_read_b32 v38, v36
	ds_read_b32 v40, v36 offset:512
	s_waitcnt lgkmcnt(1)
	v_mfma_f32_32x32x2_f32 v[78:93], v38, v130, 0
	v_mfma_f32_32x32x2_f32 v[94:109], v38, v162, 0
	ds_read_b32 v38, v36 offset:1024
	s_waitcnt lgkmcnt(1)
	v_mfma_f32_32x32x2_f32 v[78:93], v40, v131, v[78:93]
	v_mfma_f32_32x32x2_f32 v[94:109], v40, v163, v[94:109]
	ds_read_b32 v40, v36 offset:1536
	s_waitcnt lgkmcnt(1)
	v_mfma_f32_32x32x2_f32 v[78:93], v38, v132, v[78:93]
	v_mfma_f32_32x32x2_f32 v[94:109], v38, v164, v[94:109]
	ds_read_b32 v38, v36 offset:2048
	s_waitcnt lgkmcnt(1)
	v_mfma_f32_32x32x2_f32 v[78:93], v40, v133, v[78:93]
	v_mfma_f32_32x32x2_f32 v[94:109], v40, v165, v[94:109]
	ds_read_b32 v40, v36 offset:2560
	s_waitcnt lgkmcnt(1)
	v_mfma_f32_32x32x2_f32 v[78:93], v38, v134, v[78:93]
	v_mfma_f32_32x32x2_f32 v[94:109], v38, v166, v[94:109]
	ds_read_b32 v38, v36 offset:3072
	s_waitcnt lgkmcnt(1)
	v_mfma_f32_32x32x2_f32 v[78:93], v40, v135, v[78:93]
	v_mfma_f32_32x32x2_f32 v[94:109], v40, v167, v[94:109]
	ds_read_b32 v40, v36 offset:3584
	s_waitcnt lgkmcnt(1)
	v_mfma_f32_32x32x2_f32 v[78:93], v38, v136, v[78:93]
	v_mfma_f32_32x32x2_f32 v[94:109], v38, v168, v[94:109]
	ds_read_b32 v38, v36 offset:4096
	s_waitcnt lgkmcnt(1)
	v_mfma_f32_32x32x2_f32 v[78:93], v40, v137, v[78:93]
	v_mfma_f32_32x32x2_f32 v[94:109], v40, v169, v[94:109]
	ds_read_b32 v40, v36 offset:4608
	s_waitcnt lgkmcnt(1)
; __device__ __forceinline__ void phase_prep(const Params& P, int l, unsigned char* lds) {
;     ...
;             const float* ub = U + t8 * 256 + g * 64;
;             const float* ub2 = is_ctx ? ub : ub + 64 * 256;
; #pragma unroll 2
;             for (int c = 0; c < 64; ++c) {
;                 float cv[4], sv[4];
; #pragma unroll
;                 for (int q = 0; q < 4; ++q) { const float rev = (float)((c * (cp0 + q)) & 63) * (1.0f / 64.0f); cv[q] = __builtin_amdgcn_cosf(rev) * 0.125f; sv[q] = __builtin_amdgcn_sinf(rev) * 0.125f; }
; #pragma unroll
;                 for (int t = 0; t < 8; ++t) { const float u = ub[t * 256 + c], u2 = ub2[t * 256 + c];
; #pragma unroll
;                     for (int q = 0; q < 4; ++q) { aC[q][t] += u * cv[q]; aS[q][t] += u2 * ((t == 0 && sp0) ? cv[q] : sv[q]); } }
	v_mfma_f32_32x32x2_f32 v[78:93], v38, v138, v[78:93]
	v_mfma_f32_32x32x2_f32 v[94:109], v38, v170, v[94:109]
	ds_read_b32 v38, v36 offset:5120
	s_waitcnt lgkmcnt(1)
	v_mfma_f32_32x32x2_f32 v[78:93], v40, v139, v[78:93]
	v_mfma_f32_32x32x2_f32 v[94:109], v40, v171, v[94:109]
	ds_read_b32 v40, v36 offset:5632
	s_waitcnt lgkmcnt(1)
	v_mfma_f32_32x32x2_f32 v[78:93], v38, v140, v[78:93]
	v_mfma_f32_32x32x2_f32 v[94:109], v38, v172, v[94:109]
	ds_read_b32 v38, v36 offset:6144
	s_waitcnt lgkmcnt(1)
	v_mfma_f32_32x32x2_f32 v[78:93], v40, v141, v[78:93]
	v_mfma_f32_32x32x2_f32 v[94:109], v40, v173, v[94:109]
	ds_read_b32 v40, v36 offset:6656
	s_waitcnt lgkmcnt(1)
	v_mfma_f32_32x32x2_f32 v[78:93], v38, v142, v[78:93]
	v_mfma_f32_32x32x2_f32 v[94:109], v38, v174, v[94:109]
	ds_read_b32 v38, v36 offset:7168
	s_waitcnt lgkmcnt(1)
	v_mfma_f32_32x32x2_f32 v[78:93], v40, v143, v[78:93]
	v_mfma_f32_32x32x2_f32 v[94:109], v40, v175, v[94:109]
	ds_read_b32 v40, v36 offset:7680
	s_waitcnt lgkmcnt(1)
	v_mfma_f32_32x32x2_f32 v[78:93], v38, v144, v[78:93]
	v_mfma_f32_32x32x2_f32 v[94:109], v38, v176, v[94:109]
	ds_read_b32 v38, v36 offset:8192
	s_waitcnt lgkmcnt(1)
	v_mfma_f32_32x32x2_f32 v[78:93], v40, v145, v[78:93]
	v_mfma_f32_32x32x2_f32 v[94:109], v40, v177, v[94:109]
	ds_read_b32 v40, v36 offset:8704
	s_waitcnt lgkmcnt(1)
	v_mfma_f32_32x32x2_f32 v[78:93], v38, v146, v[78:93]
	v_mfma_f32_32x32x2_f32 v[94:109], v38, v178, v[94:109]
	ds_read_b32 v38, v36 offset:9216
	s_waitcnt lgkmcnt(1)
	v_mfma_f32_32x32x2_f32 v[78:93], v40, v147, v[78:93]
	v_mfma_f32_32x32x2_f32 v[94:109], v40, v179, v[94:109]
	ds_read_b32 v40, v36 offset:9728
	s_waitcnt lgkmcnt(1)
	v_mfma_f32_32x32x2_f32 v[78:93], v38, v148, v[78:93]
	v_mfma_f32_32x32x2_f32 v[94:109], v38, v180, v[94:109]
	ds_read_b32 v38, v36 offset:10240
	s_waitcnt lgkmcnt(1)
	v_mfma_f32_32x32x2_f32 v[78:93], v40, v149, v[78:93]
	v_mfma_f32_32x32x2_f32 v[94:109], v40, v181, v[94:109]
	ds_read_b32 v40, v36 offset:10752
	s_waitcnt lgkmcnt(1)
	v_mfma_f32_32x32x2_f32 v[78:93], v38, v150, v[78:93]
	v_mfma_f32_32x32x2_f32 v[94:109], v38, v182, v[94:109]
	ds_read_b32 v38, v36 offset:11264
	s_waitcnt lgkmcnt(1)
	v_mfma_f32_32x32x2_f32 v[78:93], v40, v151, v[78:93]
	v_mfma_f32_32x32x2_f32 v[94:109], v40, v183, v[94:109]
	ds_read_b32 v40, v36 offset:11776
	s_waitcnt lgkmcnt(1)
	v_mfma_f32_32x32x2_f32 v[78:93], v38, v152, v[78:93]
	v_mfma_f32_32x32x2_f32 v[94:109], v38, v184, v[94:109]
	ds_read_b32 v38, v36 offset:12288
	s_waitcnt lgkmcnt(1)
	v_mfma_f32_32x32x2_f32 v[78:93], v40, v153, v[78:93]
	v_mfma_f32_32x32x2_f32 v[94:109], v40, v185, v[94:109]
	ds_read_b32 v40, v36 offset:12800
	s_waitcnt lgkmcnt(1)
	v_mfma_f32_32x32x2_f32 v[78:93], v38, v154, v[78:93]
	v_mfma_f32_32x32x2_f32 v[94:109], v38, v186, v[94:109]
	ds_read_b32 v38, v36 offset:13312
	s_waitcnt lgkmcnt(1)
	v_mfma_f32_32x32x2_f32 v[78:93], v40, v155, v[78:93]
	v_mfma_f32_32x32x2_f32 v[94:109], v40, v187, v[94:109]
	ds_read_b32 v40, v36 offset:13824
	s_waitcnt lgkmcnt(1)
	v_mfma_f32_32x32x2_f32 v[78:93], v38, v156, v[78:93]
	v_mfma_f32_32x32x2_f32 v[94:109], v38, v188, v[94:109]
	ds_read_b32 v38, v36 offset:14336
	s_waitcnt lgkmcnt(1)
	v_mfma_f32_32x32x2_f32 v[78:93], v40, v157, v[78:93]
	v_mfma_f32_32x32x2_f32 v[94:109], v40, v189, v[94:109]
	ds_read_b32 v40, v36 offset:14848
	s_waitcnt lgkmcnt(1)
	v_mfma_f32_32x32x2_f32 v[78:93], v38, v158, v[78:93]
	v_mfma_f32_32x32x2_f32 v[94:109], v38, v190, v[94:109]
	ds_read_b32 v38, v36 offset:15360
	s_waitcnt lgkmcnt(1)
	v_mfma_f32_32x32x2_f32 v[78:93], v40, v159, v[78:93]
	v_mfma_f32_32x32x2_f32 v[94:109], v40, v191, v[94:109]
	ds_read_b32 v40, v36 offset:15872
	s_waitcnt lgkmcnt(1)
	v_mfma_f32_32x32x2_f32 v[78:93], v38, v160, v[78:93]
	v_mfma_f32_32x32x2_f32 v[94:109], v38, v192, v[94:109]
	s_waitcnt lgkmcnt(0)
	v_mfma_f32_32x32x2_f32 v[78:93], v40, v161, v[78:93]
	v_mfma_f32_32x32x2_f32 v[94:109], v40, v193, v[94:109]
	s_nop 15
	s_nop 7
	v_cmp_gt_u32_e32 vcc, 32, v32
	s_nop 1
	v_cndmask_b32_e32 v46, v46, v78, vcc
	v_cndmask_b32_e32 v62, v62, v94, vcc
; __device__ __forceinline__ unsigned pk2(float lo, float hi) { f32x2_t v = {lo, hi}; bf16x2_t b = __builtin_convertvector(v, bf16x2_t); return __builtin_bit_cast(unsigned, b); }
; __device__ __forceinline__ void phase_prep(const Params& P, int l, unsigned char* lds) {
;     ...
; #pragma unroll
;             for (int q = 0; q < 4; ++q) {
;                 const int n = n0 + q;
;                 bf16_t* dC; bf16_t* dS;
;                 if (is_ctx) { bf16_t* z = (bf16_t*)(P.ws + WS_ZCT) + ((size_t)b * 256 + n) * 512 + t0 + t8; dC = z; dS = z + 256; }
;                 else { bf16_t* z = (bf16_t*)(P.ws + WS_ZT) + ((size_t)b * 256 + n) * 2048 + (t0 - CTX) + t8; dC = z; dS = z + 1024; }
;                 u32x4 o; o.x = pk2(aC[q][0], aC[q][1]); o.y = pk2(aC[q][2], aC[q][3]); o.z = pk2(aC[q][4], aC[q][5]); o.w = pk2(aC[q][6], aC[q][7]);
;                 *(u32x4*)dC = o;
;                 u32x4 s4; s4.x = pk2(aS[q][0], aS[q][1]); s4.y = pk2(aS[q][2], aS[q][3]); s4.z = pk2(aS[q][4], aS[q][5]); s4.w = pk2(aS[q][6], aS[q][7]);
;                 *(u32x4*)dS = s4;
;             }
;             __syncthreads();
.Ldft_nosp:
	s_and_b64 vcc, exec, s[42:43]
	s_cbranch_vccz .Ldft_out_ctx
	s_nop 15
	s_nop 7
	s_lshl_b32 s7, s36, 8
	s_lshl_b32 s18, s15, 6
	s_add_u32 s7, s7, s18
	s_mul_i32 s7, s7, 4096
	s_sub_u32 s18, s64, 256
	s_lshl_b32 s19, s13, 5
	s_add_u32 s18, s18, s19
	s_lshl_b32 s18, s18, 1
	s_add_u32 s7, s7, s18
	s_add_u32 s40, s0, s7
	s_addc_u32 s41, s1, 0
	s_add_u32 s40, s40, 0x17e00000
	s_addc_u32 s41, s41, 0
	v_lshlrev_b32_e32 v124, 12, v34
	v_lshl_add_u32 v124, v33, 3, v124
	v_add_u32_e32 v125, 0x20000, v124
	v_cvt_pk_bf16_f32 v126, v0, v1
	v_cvt_pk_bf16_f32 v127, v2, v3
	global_store_dwordx2 v124, v[126:127], s[40:41]
	v_cvt_pk_bf16_f32 v126, v4, v5
	v_cvt_pk_bf16_f32 v127, v6, v7
	global_store_dwordx2 v124, v[126:127], s[40:41] offset:16
	v_cvt_pk_bf16_f32 v126, v8, v9
	v_cvt_pk_bf16_f32 v127, v10, v11
	global_store_dwordx2 v124, v[126:127], s[40:41] offset:32
	v_cvt_pk_bf16_f32 v126, v12, v13
	v_cvt_pk_bf16_f32 v127, v14, v15
	global_store_dwordx2 v124, v[126:127], s[40:41] offset:48
	v_cvt_pk_bf16_f32 v126, v16, v17
	v_cvt_pk_bf16_f32 v127, v18, v19
	global_store_dwordx2 v125, v[126:127], s[40:41]
	v_cvt_pk_bf16_f32 v126, v20, v21
	v_cvt_pk_bf16_f32 v127, v22, v23
	global_store_dwordx2 v125, v[126:127], s[40:41] offset:16
	v_cvt_pk_bf16_f32 v126, v24, v25
	v_cvt_pk_bf16_f32 v127, v26, v27
	global_store_dwordx2 v125, v[126:127], s[40:41] offset:32
	v_cvt_pk_bf16_f32 v126, v28, v29
	v_cvt_pk_bf16_f32 v127, v30, v31
	global_store_dwordx2 v125, v[126:127], s[40:41] offset:48
	v_cvt_pk_bf16_f32 v126, v46, v47
	v_cvt_pk_bf16_f32 v127, v48, v49
	global_store_dwordx2 v124, v[126:127], s[40:41] offset:2048
	v_cvt_pk_bf16_f32 v126, v50, v51
	v_cvt_pk_bf16_f32 v127, v52, v53
	global_store_dwordx2 v124, v[126:127], s[40:41] offset:2064
	v_cvt_pk_bf16_f32 v126, v54, v55
	v_cvt_pk_bf16_f32 v127, v56, v57
	global_store_dwordx2 v124, v[126:127], s[40:41] offset:2080
	v_cvt_pk_bf16_f32 v126, v58, v59
	v_cvt_pk_bf16_f32 v127, v60, v61
	global_store_dwordx2 v124, v[126:127], s[40:41] offset:2096
	v_cvt_pk_bf16_f32 v126, v62, v63
	v_cvt_pk_bf16_f32 v127, v64, v65
	global_store_dwordx2 v125, v[126:127], s[40:41] offset:2048
	v_cvt_pk_bf16_f32 v126, v66, v67
	v_cvt_pk_bf16_f32 v127, v68, v69
	global_store_dwordx2 v125, v[126:127], s[40:41] offset:2064
	v_cvt_pk_bf16_f32 v126, v70, v71
	v_cvt_pk_bf16_f32 v127, v72, v73
	global_store_dwordx2 v125, v[126:127], s[40:41] offset:2080
	v_cvt_pk_bf16_f32 v126, v74, v75
	v_cvt_pk_bf16_f32 v127, v76, v77
	global_store_dwordx2 v125, v[126:127], s[40:41] offset:2096
	s_branch .Ldft_out_done
.Ldft_out_ctx:
	s_nop 15
	s_nop 7
	s_lshl_b32 s7, s36, 8
	s_lshl_b32 s18, s15, 6
	s_add_u32 s7, s7, s18
	s_mul_i32 s7, s7, 1024
	s_sub_u32 s18, s64, 0
	s_lshl_b32 s19, s13, 5
	s_add_u32 s18, s18, s19
	s_lshl_b32 s18, s18, 1
	s_add_u32 s7, s7, s18
	s_add_u32 s40, s0, s7
	s_addc_u32 s41, s1, 0
	s_add_u32 s40, s40, 0x19e00000
	s_addc_u32 s41, s41, 0
	v_lshlrev_b32_e32 v124, 10, v34
	v_lshl_add_u32 v124, v33, 3, v124
	v_add_u32_e32 v125, 0x8000, v124
	v_cvt_pk_bf16_f32 v126, v0, v1
	v_cvt_pk_bf16_f32 v127, v2, v3
	global_store_dwordx2 v124, v[126:127], s[40:41]
	v_cvt_pk_bf16_f32 v126, v4, v5
	v_cvt_pk_bf16_f32 v127, v6, v7
	global_store_dwordx2 v124, v[126:127], s[40:41] offset:16
	v_cvt_pk_bf16_f32 v126, v8, v9
	v_cvt_pk_bf16_f32 v127, v10, v11
	global_store_dwordx2 v124, v[126:127], s[40:41] offset:32
	v_cvt_pk_bf16_f32 v126, v12, v13
	v_cvt_pk_bf16_f32 v127, v14, v15
	global_store_dwordx2 v124, v[126:127], s[40:41] offset:48
	v_cvt_pk_bf16_f32 v126, v16, v17
	v_cvt_pk_bf16_f32 v127, v18, v19
	global_store_dwordx2 v125, v[126:127], s[40:41]
	v_cvt_pk_bf16_f32 v126, v20, v21
	v_cvt_pk_bf16_f32 v127, v22, v23
	global_store_dwordx2 v125, v[126:127], s[40:41] offset:16
	v_cvt_pk_bf16_f32 v126, v24, v25
	v_cvt_pk_bf16_f32 v127, v26, v27
	global_store_dwordx2 v125, v[126:127], s[40:41] offset:32
	v_cvt_pk_bf16_f32 v126, v28, v29
	v_cvt_pk_bf16_f32 v127, v30, v31
	global_store_dwordx2 v125, v[126:127], s[40:41] offset:48
	v_cvt_pk_bf16_f32 v126, v46, v47
	v_cvt_pk_bf16_f32 v127, v48, v49
	global_store_dwordx2 v124, v[126:127], s[40:41] offset:512
	v_cvt_pk_bf16_f32 v126, v50, v51
	v_cvt_pk_bf16_f32 v127, v52, v53
	global_store_dwordx2 v124, v[126:127], s[40:41] offset:528
	v_cvt_pk_bf16_f32 v126, v54, v55
	v_cvt_pk_bf16_f32 v127, v56, v57
	global_store_dwordx2 v124, v[126:127], s[40:41] offset:544
	v_cvt_pk_bf16_f32 v126, v58, v59
	v_cvt_pk_bf16_f32 v127, v60, v61
	global_store_dwordx2 v124, v[126:127], s[40:41] offset:560
	v_cvt_pk_bf16_f32 v126, v62, v63
	v_cvt_pk_bf16_f32 v127, v64, v65
	global_store_dwordx2 v125, v[126:127], s[40:41] offset:512
	v_cvt_pk_bf16_f32 v126, v66, v67
	v_cvt_pk_bf16_f32 v127, v68, v69
	global_store_dwordx2 v125, v[126:127], s[40:41] offset:528
	v_cvt_pk_bf16_f32 v126, v70, v71
	v_cvt_pk_bf16_f32 v127, v72, v73
	global_store_dwordx2 v125, v[126:127], s[40:41] offset:544
	v_cvt_pk_bf16_f32 v126, v74, v75
	v_cvt_pk_bf16_f32 v127, v76, v77
	global_store_dwordx2 v125, v[126:127], s[40:41] offset:560
.Ldft_out_done:
	s_mov_b64 s[38:39], 0
	s_barrier
